# h0 row loop software-pipelined by hand: next row requested before the current row is normalised; the end-of-iteration wait leaves the stores in flight
# baseline (speedup 1.0000x reference)
.LBB0_29:
	s_or_b64 exec, exec, s[4:5]
	s_waitcnt lgkmcnt(0)
	s_barrier
	ds_read_b64 v[0:1], v41
	s_waitcnt lgkmcnt(0)
	s_barrier
	v_readlane_b32 s4, v253, 29
	v_readfirstlane_b32 s23, v0
	v_mbcnt_lo_u32_b32 v0, -1, 0
	v_mbcnt_hi_u32_b32 v0, -1, v0
	v_readfirstlane_b32 s24, v1
	v_or_b32_e32 v0, s55, v0
	v_ashrrev_i32_e32 v1, 6, v0
	v_add_u32_e32 v32, s4, v1
	s_movk_i32 s4, 0x4000
	v_mbcnt_lo_u32_b32 v0, -1, 0
	v_mbcnt_hi_u32_b32 v0, -1, v0
	v_cmp_gt_i32_e32 vcc, s4, v32
	s_mov_b64 s[6:7], exec
	s_and_b64 s[4:5], s[6:7], vcc
	s_waitcnt vmcnt(3)
	v_mov_b32_e32 v84, 0x358637bd
	s_mov_b64 exec, s[4:5]
	s_cbranch_execz .LBB0_32
	v_lshlrev_b32_e32 v0, 2, v0
	v_and_b32_e32 v33, 0xfc, v0
	v_lshlrev_b32_e32 v40, 2, v33
	v_readlane_b32 s4, v253, 30
	v_readlane_b32 s8, v253, 32
	v_readlane_b32 s36, v255, 5
	v_readlane_b32 s5, v253, 31
	v_readlane_b32 s9, v253, 33
	v_or_b32_e32 v8, 0x400, v40
	s_waitcnt vmcnt(0)
	v_or_b32_e32 v12, 0x800, v40
	v_or_b32_e32 v28, 0xc00, v40
	v_readlane_b32 s46, v255, 15
	v_readlane_b32 s47, v255, 16
	global_load_dwordx4 v[0:3], v40, s[4:5]
	global_load_dwordx4 v[42:45], v40, s[8:9]
	global_load_dwordx4 v[4:7], v8, s[4:5]
	global_load_dwordx4 v[46:49], v8, s[8:9]
	s_nop 0
	global_load_dwordx4 v[8:11], v12, s[4:5]
	global_load_dwordx4 v[50:53], v12, s[8:9]
	global_load_dwordx4 v[54:57], v28, s[8:9]
	s_nop 0
	global_load_dwordx4 v[12:15], v40, s[46:47]
	global_load_dwordx4 v[16:19], v40, s[46:47] offset:1024
	global_load_dwordx4 v[20:23], v40, s[46:47] offset:2048
	global_load_dwordx4 v[24:27], v40, s[46:47] offset:3072
	s_nop 0
	global_load_dwordx4 v[28:31], v28, s[4:5]
	v_readlane_b32 s37, v255, 6
	v_readlane_b32 s4, v253, 27
	v_readlane_b32 s5, v253, 28
	v_lshl_add_u64 v[34:35], s[36:37], 0, v[40:41]
	v_lshlrev_b32_e32 v40, 1, v33
	v_lshl_add_u64 v[36:37], s[4:5], 0, v[40:41]
	s_mov_b64 s[8:9], 0
	v_readlane_b32 s38, v255, 7
	v_readlane_b32 s39, v255, 8
	v_readlane_b32 s40, v255, 9
	v_readlane_b32 s41, v255, 10
	v_readlane_b32 s42, v255, 11
	v_readlane_b32 s43, v255, 12
	v_readlane_b32 s44, v255, 13
	v_readlane_b32 s45, v255, 14
	v_readlane_b32 s48, v255, 17
	v_readlane_b32 s49, v255, 18
	v_readlane_b32 s50, v255, 19
	v_readlane_b32 s51, v255, 20
	s_waitcnt vmcnt(10)
	v_pk_add_f32 v[38:39], v[42:43], 1.0 op_sel_hi:[1,0]
	v_pk_add_f32 v[42:43], v[44:45], 1.0 op_sel_hi:[1,0]
	s_waitcnt vmcnt(8)
	v_pk_add_f32 v[44:45], v[46:47], 1.0 op_sel_hi:[1,0]
	v_pk_add_f32 v[46:47], v[48:49], 1.0 op_sel_hi:[1,0]
	s_waitcnt vmcnt(6)
	v_pk_add_f32 v[48:49], v[50:51], 1.0 op_sel_hi:[1,0]
	v_pk_add_f32 v[50:51], v[52:53], 1.0 op_sel_hi:[1,0]
	s_waitcnt vmcnt(5)
	v_pk_add_f32 v[52:53], v[54:55], 1.0 op_sel_hi:[1,0]
	v_pk_add_f32 v[54:55], v[56:57], 1.0 op_sel_hi:[1,0]
	v_ashrrev_i32_e32 v33, 31, v32
	v_lshlrev_b64 v[74:75], 12, v[32:33]
	v_lshl_add_u64 v[76:77], v[34:35], 0, v[74:75]
	global_load_dwordx4 v[200:203], v[76:77], off
	global_load_dwordx4 v[204:207], v[76:77], off offset:2048
	global_load_dwordx4 v[208:211], v[76:77], off offset:3072
	global_load_dwordx4 v[212:215], v[76:77], off offset:1024
	s_waitcnt vmcnt(0)
.LBB0_31:
	v_mov_b32_e32 v56, v200
	v_mov_b32_e32 v57, v201
	v_mov_b32_e32 v58, v202
	v_mov_b32_e32 v59, v203
	v_mov_b32_e32 v60, v204
	v_mov_b32_e32 v61, v205
	v_mov_b32_e32 v62, v206
	v_mov_b32_e32 v63, v207
	v_mov_b32_e32 v64, v208
	v_mov_b32_e32 v65, v209
	v_mov_b32_e32 v66, v210
	v_mov_b32_e32 v67, v211
	v_mov_b32_e32 v68, v212
	v_mov_b32_e32 v69, v213
	v_mov_b32_e32 v70, v214
	v_mov_b32_e32 v71, v215
	v_mad_i64_i32 v[72:73], s[4:5], v32, s33, v[36:37]
	v_add_u32_e32 v32, s60, v32
	v_cmp_lt_i32_e64 s[4:5], s66, v32
	s_or_b64 s[8:9], s[4:5], s[8:9]
	s_mov_b64 s[10:11], exec
	s_andn2_b64 exec, exec, s[8:9]
	v_ashrrev_i32_e32 v33, 31, v32
	v_lshlrev_b64 v[74:75], 12, v[32:33]
	v_lshl_add_u64 v[76:77], v[34:35], 0, v[74:75]
	global_load_dwordx4 v[200:203], v[76:77], off
	global_load_dwordx4 v[204:207], v[76:77], off offset:2048
	global_load_dwordx4 v[208:211], v[76:77], off offset:3072
	global_load_dwordx4 v[212:215], v[76:77], off offset:1024
	s_mov_b64 exec, s[10:11]
	v_mul_f32_e32 v33, v57, v57
	v_fmac_f32_e32 v33, v56, v56
	v_fmac_f32_e32 v33, v58, v58
	v_fmac_f32_e32 v33, v59, v59
	v_fmac_f32_e32 v33, v68, v68
	v_fmac_f32_e32 v33, v69, v69
	v_fmac_f32_e32 v33, v70, v70
	v_fmac_f32_e32 v33, v71, v71
	v_fmac_f32_e32 v33, v60, v60
	v_pk_mul_f32 v[74:75], v[62:63], v[62:63]
	v_fmac_f32_e32 v33, v61, v61
	v_add_f32_e32 v33, v74, v33
	v_pk_mul_f32 v[78:79], v[64:65], v[64:65]
	v_add_f32_e32 v33, v75, v33
	v_add_f32_e32 v33, v78, v33
	v_pk_mul_f32 v[76:77], v[66:67], v[66:67]
	v_add_f32_e32 v33, v79, v33
	v_add_f32_e32 v33, v76, v33
	v_add_f32_e32 v33, v77, v33
	s_nop 1
	v_add_f32_dpp v33, v33, v33 quad_perm:[1,0,3,2] row_mask:0xf bank_mask:0xf bound_ctrl:1
	s_nop 1
	v_add_f32_dpp v33, v33, v33 quad_perm:[2,3,0,1] row_mask:0xf bank_mask:0xf bound_ctrl:1
	s_nop 1
	v_add_f32_dpp v33, v33, v33 row_half_mirror row_mask:0xf bank_mask:0xf bound_ctrl:1
	s_nop 1
	v_add_f32_dpp v33, v33, v33 row_mirror row_mask:0xf bank_mask:0xf bound_ctrl:1
	s_nop 0
	v_readlane_b32 s10, v33, 16
	v_readlane_b32 s11, v33, 48
	v_readlane_b32 s4, v33, 0
	v_readlane_b32 s5, v33, 32
	v_mov_b32_e32 v74, s10
	v_mov_b32_e32 v75, s11
	v_pk_add_f32 v[74:75], s[4:5], v[74:75]
	v_add_f32_e32 v33, v74, v75
	v_fmamk_f32 v33, v33, 0x3a800000, v84
	v_mul_f32_e32 v40, 0x4b800000, v33
	v_cmp_gt_f32_e32 vcc, s70, v33
	s_nop 0
	v_cndmask_b32_e32 v33, v33, v40, vcc
	v_rsq_f32_e32 v33, v33
	s_nop 0
	v_mul_f32_e32 v40, 0x45800000, v33
	v_cndmask_b32_e32 v40, v33, v40, vcc
	v_pk_mul_f32 v[56:57], v[56:57], v[40:41] op_sel_hi:[1,0]
	v_pk_mul_f32 v[58:59], v[58:59], v[40:41] op_sel_hi:[1,0]
	v_pk_mul_f32 v[68:69], v[68:69], v[40:41] op_sel_hi:[1,0]
	v_pk_mul_f32 v[70:71], v[70:71], v[40:41] op_sel_hi:[1,0]
	v_pk_mul_f32 v[60:61], v[60:61], v[40:41] op_sel_hi:[1,0]
	v_pk_mul_f32 v[62:63], v[62:63], v[40:41] op_sel_hi:[1,0]
	v_pk_mul_f32 v[64:65], v[64:65], v[40:41] op_sel_hi:[1,0]
	v_pk_mul_f32 v[66:67], v[66:67], v[40:41] op_sel_hi:[1,0]
	v_pk_mul_f32 v[56:57], v[12:13], v[56:57]
	v_pk_mul_f32 v[58:59], v[14:15], v[58:59]
	v_pk_mul_f32 v[68:69], v[16:17], v[68:69]
	v_pk_mul_f32 v[70:71], v[18:19], v[70:71]
	v_pk_mul_f32 v[60:61], v[20:21], v[60:61]
	v_pk_mul_f32 v[62:63], v[22:23], v[62:63]
	v_pk_mul_f32 v[64:65], v[24:25], v[64:65]
	v_pk_mul_f32 v[66:67], v[26:27], v[66:67]
	v_pk_fma_f32 v[56:57], v[38:39], v[56:57], v[0:1]
	v_pk_fma_f32 v[58:59], v[42:43], v[58:59], v[2:3]
	v_pk_fma_f32 v[68:69], v[44:45], v[68:69], v[4:5]
	v_pk_fma_f32 v[70:71], v[46:47], v[70:71], v[6:7]
	v_pk_fma_f32 v[60:61], v[48:49], v[60:61], v[8:9]
	v_pk_fma_f32 v[62:63], v[50:51], v[62:63], v[10:11]
	v_pk_fma_f32 v[64:65], v[52:53], v[64:65], v[28:29]
	v_pk_fma_f32 v[66:67], v[54:55], v[66:67], v[30:31]
	v_cvt_pk_f16_f32 v56, v56, v57
	v_cvt_pk_f16_f32 v57, v58, v59
	v_cvt_pk_f16_f32 v58, v68, v69
	v_cvt_pk_f16_f32 v59, v70, v71
	v_cvt_pk_f16_f32 v60, v60, v61
	v_cvt_pk_f16_f32 v61, v62, v63
	v_cvt_pk_f16_f32 v62, v64, v65
	v_cvt_pk_f16_f32 v63, v66, v67
	global_store_dwordx2 v[72:73], v[56:57], off
	global_store_dwordx2 v[72:73], v[58:59], off offset:512
	global_store_dwordx2 v[72:73], v[60:61], off offset:1024
	global_store_dwordx2 v[72:73], v[62:63], off offset:1536
	s_waitcnt vmcnt(4)
	s_andn2_b64 exec, exec, s[8:9]
	s_cbranch_execnz .LBB0_31
